# recurrence-interval de-serialisation: gate GEMM, compression GEMM, V-tile and gain-vector loads batched (counted waits)
# speedup vs baseline: 1.0059x; 1.0059x over previous
; #define LAS __attribute__((address_space(3)))
; #define MFMA32(a, b, c) __builtin_amdgcn_mfma_f32_32x32x16_bf16((a), (b), (c), 0, 0, 0)
; __device__ __forceinline__ void ng_phase(const bf16* u, const bf16* wt, bf16* z, LAS unsigned char* lds, int tid, int G) {
;     ...
;             for (int s = 0; s < 32; ++s) {
;                 const bf16x8 av = *(const bf16x8*)(ap + 16 * s), b0 = *(const bf16x8*)(b0p + 16 * s), b1 = *(const bf16x8*)(b1p + 16 * s);
;                 acc0 = MFMA32(b0, av, acc0); acc1 = MFMA32(b1, av, acc1);
;             }
;             LAS float* P = (LAS float*)lds + ((rbl * 4 + kq) * 2) * 1024 + lane * 16;
; #pragma unroll
;             for (int a = 0; a < 4; ++a) { *(LAS f32x4*)(P + 4 * a) = (f32x4){acc0[4 * a], acc0[4 * a + 1], acc0[4 * a + 2], acc0[4 * a + 3]};
;                                           *(LAS f32x4*)(P + 1024 + 4 * a) = (f32x4){acc1[4 * a], acc1[4 * a + 1], acc1[4 * a + 2], acc1[4 * a + 3]}; }
.LBB0_681:
	v_lshl_add_u64 v[58:59], v[42:43], 0, s[6:7]
	v_lshl_add_u64 v[60:61], v[38:39], 0, s[6:7]
	v_lshl_add_u64 v[62:63], v[36:37], 0, s[6:7]
	global_load_dwordx4 v[64:67], v[58:59], off offset:-128
	global_load_dwordx4 v[96:99], v[60:61], off offset:-128
	global_load_dwordx4 v[128:131], v[62:63], off offset:-128
	global_load_dwordx4 v[68:71], v[58:59], off offset:-96
	global_load_dwordx4 v[100:103], v[60:61], off offset:-96
	global_load_dwordx4 v[132:135], v[62:63], off offset:-96
	global_load_dwordx4 v[72:75], v[58:59], off offset:-64
	global_load_dwordx4 v[104:107], v[60:61], off offset:-64
	global_load_dwordx4 v[136:139], v[62:63], off offset:-64
	global_load_dwordx4 v[76:79], v[58:59], off offset:-32
	global_load_dwordx4 v[108:111], v[60:61], off offset:-32
	global_load_dwordx4 v[140:143], v[62:63], off offset:-32
	global_load_dwordx4 v[80:83], v[58:59], off
	global_load_dwordx4 v[112:115], v[60:61], off
	global_load_dwordx4 v[144:147], v[62:63], off
	global_load_dwordx4 v[84:87], v[58:59], off offset:32
	global_load_dwordx4 v[116:119], v[60:61], off offset:32
	global_load_dwordx4 v[148:151], v[62:63], off offset:32
	global_load_dwordx4 v[88:91], v[58:59], off offset:64
	global_load_dwordx4 v[120:123], v[60:61], off offset:64
	global_load_dwordx4 v[152:155], v[62:63], off offset:64
	global_load_dwordx4 v[92:95], v[58:59], off offset:96
	global_load_dwordx4 v[124:127], v[60:61], off offset:96
	global_load_dwordx4 v[156:159], v[62:63], off offset:96
	s_add_u32 s6, s6, 0x100
	s_addc_u32 s7, s7, 0
	s_cmpk_eq_i32 s6, 0x400
	s_waitcnt vmcnt(22)
	v_mfma_f32_32x32x16_bf16 v[4:19], v[96:99], v[64:67], v[4:19]
	s_waitcnt vmcnt(21)
	v_mfma_f32_32x32x16_bf16 v[20:35], v[128:131], v[64:67], v[20:35]
	s_waitcnt vmcnt(19)
	v_mfma_f32_32x32x16_bf16 v[4:19], v[100:103], v[68:71], v[4:19]
	s_waitcnt vmcnt(18)
	v_mfma_f32_32x32x16_bf16 v[20:35], v[132:135], v[68:71], v[20:35]
	s_waitcnt vmcnt(16)
	v_mfma_f32_32x32x16_bf16 v[4:19], v[104:107], v[72:75], v[4:19]
	s_waitcnt vmcnt(15)
	v_mfma_f32_32x32x16_bf16 v[20:35], v[136:139], v[72:75], v[20:35]
	s_waitcnt vmcnt(13)
	v_mfma_f32_32x32x16_bf16 v[4:19], v[108:111], v[76:79], v[4:19]
	s_waitcnt vmcnt(12)
	v_mfma_f32_32x32x16_bf16 v[20:35], v[140:143], v[76:79], v[20:35]
	s_waitcnt vmcnt(10)
	v_mfma_f32_32x32x16_bf16 v[4:19], v[112:115], v[80:83], v[4:19]
	s_waitcnt vmcnt(9)
	v_mfma_f32_32x32x16_bf16 v[20:35], v[144:147], v[80:83], v[20:35]
	s_waitcnt vmcnt(7)
	v_mfma_f32_32x32x16_bf16 v[4:19], v[116:119], v[84:87], v[4:19]
	s_waitcnt vmcnt(6)
	v_mfma_f32_32x32x16_bf16 v[20:35], v[148:151], v[84:87], v[20:35]
	s_waitcnt vmcnt(4)
	v_mfma_f32_32x32x16_bf16 v[4:19], v[120:123], v[88:91], v[4:19]
	s_waitcnt vmcnt(3)
	v_mfma_f32_32x32x16_bf16 v[20:35], v[152:155], v[88:91], v[20:35]
	s_waitcnt vmcnt(1)
	v_mfma_f32_32x32x16_bf16 v[4:19], v[124:127], v[92:95], v[4:19]
	s_waitcnt vmcnt(0)
	v_mfma_f32_32x32x16_bf16 v[20:35], v[156:159], v[92:95], v[20:35]
	s_cbranch_scc0 .LBB0_681
	v_add_u32_e32 v42, s8, v44
	s_mov_b64 s[6:7], s[4:5]
	s_nop 6
	ds_write_b128 v42, v[4:7]
	s_nop 0
	ds_write_b128 v42, v[20:23] offset:4096
	ds_write_b128 v42, v[8:11] offset:16
	ds_write_b128 v42, v[24:27] offset:4112
	ds_write_b128 v42, v[12:15] offset:32
	ds_write_b128 v42, v[28:31] offset:4128
	ds_write_b128 v42, v[16:19] offset:48
	ds_write_b128 v42, v[32:35] offset:4144

; __device__ __forceinline__ float bflo(unsigned w) { return __uint_as_float(w << 16); }
; __device__ __forceinline__ float bfhi(unsigned w) { return __uint_as_float(w & 0xffff0000u); }
; __device__ __forceinline__ unsigned pk2(float lo, float hi) { return pg8::cvt_pk_bf16(lo, hi); }
; __device__ __forceinline__ void norm64_inplace(bf16* p, const float* gain, float mult) {
;     u32x4 w[8]; float ss = 0.f;
; #pragma unroll
;     for (int k = 0; k < 8; ++k) { w[k] = ((const u32x4*)p)[k];
;         const float a0 = bflo(w[k].x), a1 = bfhi(w[k].x), a2 = bflo(w[k].y), a3 = bfhi(w[k].y), a4 = bflo(w[k].z), a5 = bfhi(w[k].z), a6 = bflo(w[k].w), a7 = bfhi(w[k].w);
;         ss += (a0 * a0 + a1 * a1) + (a2 * a2 + a3 * a3) + (a4 * a4 + a5 * a5) + (a6 * a6 + a7 * a7); }
;     const float r = rsqrtf(ss * (1.0f / 64.0f) + EPS) * mult;
; #pragma unroll
;     for (int k = 0; k < 8; ++k) { const f32x4 g0 = *(const f32x4*)(gain + 8 * k), g1 = *(const f32x4*)(gain + 8 * k + 4);
;         u32x4 o; o.x = pk2(bflo(w[k].x) * r * g0[0], bfhi(w[k].x) * r * g0[1]); o.y = pk2(bflo(w[k].y) * r * g0[2], bfhi(w[k].y) * r * g0[3]);
;         o.z = pk2(bflo(w[k].z) * r * g1[0], bfhi(w[k].z) * r * g1[1]); o.w = pk2(bflo(w[k].w) * r * g1[2], bfhi(w[k].w) * r * g1[3]);
;         ((u32x4*)p)[k] = o; }
; __device__ __forceinline__ void nsa_prep2_phase(bf16* z, const float* qg, const float* kg, bf16* vst, bf16* vwt, LAS unsigned char* lds, int tid, int u0, int ustride) {
;     ...
;         { const int tok = tid >> 3, wh = (tid >> 2) & 1, g = tid & 3; norm64_inplace(z + (row0 + tok) * ZP + (wh ? C_KW : C_KS) + g * 64, kg, 1.0f); }
.LBB0_687:
	s_or_b64 exec, exec, s[20:21]
	v_mad_u64_u32 v[4:5], s[4:5], v30, s88, 0
	v_mad_i32_i24 v5, v31, s88, v5
	v_lshl_add_u64 v[44:45], v[34:35], 0, v[4:5]
	global_load_dwordx4 v[8:11], v[44:45], off offset:48
	global_load_dwordx4 v[12:15], v[44:45], off offset:32
	global_load_dwordx4 v[28:31], v[44:45], off
	global_load_dwordx4 v[4:7], v[44:45], off offset:16
	s_lshl_b32 s4, s16, 2
	s_ashr_i32 s5, s4, 31
	s_lshl_b64 s[6:7], s[4:5], 18
	s_lshl_b32 s68, s1, 1
	v_mov_b32_e32 v43, v3
	s_or_b32 s16, s4, 1
	s_ashr_i32 s17, s16, 31
	s_lshl_b64 s[16:17], s[16:17], 18
	s_or_b32 s18, s4, 2
	s_ashr_i32 s19, s18, 31
	s_lshl_b64 s[18:19], s[18:19], 18
	s_or_b32 s4, s4, 3
	s_ashr_i32 s5, s4, 31
	s_lshl_b64 s[4:5], s[4:5], 18
	s_add_i32 s1, s0, 0x80
	s_cmpk_gt_i32 s0, 0x7f
	s_waitcnt vmcnt(3)
	v_lshlrev_b32_e32 v113, 16, v8
	s_waitcnt vmcnt(2)
	v_lshlrev_b32_e32 v58, 16, v12
	v_and_b32_e32 v59, 0xffff0000, v12
	s_waitcnt vmcnt(0)
	v_and_b32_e32 v63, 0xffff0000, v5
	v_and_b32_e32 v62, 0xffff0000, v4
	v_lshlrev_b32_e32 v79, 16, v5
	v_lshlrev_b32_e32 v78, 16, v4
	v_pk_mul_f32 v[4:5], v[62:63], v[62:63]
	v_and_b32_e32 v61, 0xffff0000, v7
	v_and_b32_e32 v60, 0xffff0000, v6
	v_pk_fma_f32 v[4:5], v[78:79], v[78:79], v[4:5]
	v_lshlrev_b32_e32 v81, 16, v7
	v_lshlrev_b32_e32 v80, 16, v6
	v_pk_mul_f32 v[6:7], v[60:61], v[60:61]
	v_pk_add_f32 v[4:5], v[4:5], v[4:5] op_sel:[0,1] op_sel_hi:[1,0]
	v_pk_fma_f32 v[6:7], v[80:81], v[80:81], v[6:7]
	v_lshlrev_b32_e32 v56, 16, v13
	v_pk_add_f32 v[4:5], v[6:7], v[4:5]
	v_and_b32_e32 v57, 0xffff0000, v13
	v_pk_add_f32 v[68:69], v[6:7], v[4:5] op_sel:[1,0] op_sel_hi:[0,1]
	global_load_dwordx4 v[4:7], v[44:45], off offset:112
	global_load_dwordx4 v[16:19], v[44:45], off offset:96
	global_load_dwordx4 v[20:23], v[44:45], off offset:80
	global_load_dwordx4 v[24:27], v[44:45], off offset:64
	v_mul_f32_e32 v2, v59, v59
	v_pk_fma_f32 v[64:65], v[58:59], v[58:59], v[2:3] op_sel_hi:[1,1,0]
	v_mul_f32_e32 v2, v57, v57
	v_pk_fma_f32 v[66:67], v[56:57], v[56:57], v[2:3] op_sel_hi:[1,1,0]
	v_and_b32_e32 v95, 0xffff0000, v31
	v_and_b32_e32 v97, 0xffff0000, v30
	v_and_b32_e32 v101, 0xffff0000, v28
	v_lshlrev_b32_e32 v94, 16, v31
	v_lshlrev_b32_e32 v96, 16, v30
	v_and_b32_e32 v99, 0xffff0000, v29
	v_lshlrev_b32_e32 v100, 16, v28
	v_mov_b32_e32 v30, v97
	v_mov_b32_e32 v31, v101
	v_lshlrev_b32_e32 v98, 16, v29
	v_mov_b32_e32 v28, v96
	v_mov_b32_e32 v29, v100
	v_pk_mul_f32 v[30:31], v[30:31], v[30:31]
	v_mov_b32_e32 v106, v80
	v_pk_fma_f32 v[28:29], v[28:29], v[28:29], v[30:31]
	v_mov_b32_e32 v107, v60
	v_mov_b32_e32 v60, v81
	v_lshlrev_b32_e32 v80, 16, v9
	v_and_b32_e32 v81, 0xffff0000, v9
	v_and_b32_e32 v93, 0xffff0000, v8
	v_and_b32_e32 v92, 0xffff0000, v14
	v_pk_mul_f32 v[8:9], v[80:81], v[80:81]
	v_lshlrev_b32_e32 v112, 16, v14
	v_lshlrev_b32_e32 v115, 16, v10
	v_lshlrev_b32_e32 v114, 16, v15
	v_mov_b32_e32 v110, v78
	v_lshlrev_b32_e32 v78, 16, v11
	v_mov_b32_e32 v65, v8
	v_mov_b32_e32 v67, v9
	v_mov_b32_e32 v111, v62
	v_mov_b32_e32 v62, v79
	v_pk_add_f32 v[8:9], v[64:65], v[66:67]
	v_mov_b32_e32 v104, v112
	v_mov_b32_e32 v105, v92
	s_waitcnt vmcnt(2)
	v_and_b32_e32 v47, 0xffff0000, v16
	s_waitcnt vmcnt(1)
	v_and_b32_e32 v51, 0xffff0000, v21
	s_waitcnt vmcnt(0)
	v_and_b32_e32 v55, 0xffff0000, v25
	v_and_b32_e32 v54, 0xffff0000, v24
	v_lshlrev_b32_e32 v83, 16, v25
	v_lshlrev_b32_e32 v82, 16, v24
	v_pk_mul_f32 v[12:13], v[54:55], v[54:55]
	v_and_b32_e32 v53, 0xffff0000, v27
	v_and_b32_e32 v52, 0xffff0000, v26
	v_pk_fma_f32 v[12:13], v[82:83], v[82:83], v[12:13]
	v_lshlrev_b32_e32 v85, 16, v27
	v_lshlrev_b32_e32 v84, 16, v26
	v_pk_mul_f32 v[24:25], v[52:53], v[52:53]
	v_pk_add_f32 v[12:13], v[12:13], v[12:13] op_sel:[0,1] op_sel_hi:[1,0]
	v_pk_fma_f32 v[24:25], v[84:85], v[84:85], v[24:25]
	v_and_b32_e32 v50, 0xffff0000, v20
	v_pk_add_f32 v[12:13], v[24:25], v[12:13]
	v_lshlrev_b32_e32 v87, 16, v21
	v_pk_add_f32 v[70:71], v[24:25], v[12:13] op_sel:[1,0] op_sel_hi:[0,1]
	v_lshlrev_b32_e32 v86, 16, v20
	v_pk_mul_f32 v[12:13], v[50:51], v[50:51]
	v_and_b32_e32 v49, 0xffff0000, v23
	v_and_b32_e32 v48, 0xffff0000, v22
	v_pk_fma_f32 v[12:13], v[86:87], v[86:87], v[12:13]
	v_lshlrev_b32_e32 v89, 16, v23
	v_lshlrev_b32_e32 v88, 16, v22
	v_pk_mul_f32 v[20:21], v[48:49], v[48:49]
	v_pk_add_f32 v[12:13], v[12:13], v[12:13] op_sel:[0,1] op_sel_hi:[1,0]
	v_pk_fma_f32 v[20:21], v[88:89], v[88:89], v[20:21]
	v_lshlrev_b32_e32 v46, 16, v16
	v_pk_add_f32 v[12:13], v[20:21], v[12:13]
	v_mul_f32_e32 v2, v47, v47
	v_pk_add_f32 v[76:77], v[20:21], v[12:13] op_sel:[1,0] op_sel_hi:[0,1]
	global_load_dwordx4 v[130:133], v3, s[10:11]
	global_load_dwordx4 v[134:137], v3, s[10:11] offset:16
	global_load_dwordx4 v[138:141], v3, s[10:11] offset:32
	global_load_dwordx4 v[142:145], v3, s[10:11] offset:48
	global_load_dwordx4 v[146:149], v3, s[10:11] offset:64
	global_load_dwordx4 v[150:153], v3, s[10:11] offset:80
	global_load_dwordx4 v[154:157], v3, s[10:11] offset:96
	global_load_dwordx4 v[158:161], v3, s[10:11] offset:112
	global_load_dwordx4 v[162:165], v3, s[10:11] offset:128
	global_load_dwordx4 v[166:169], v3, s[10:11] offset:144
	global_load_dwordx4 v[170:173], v3, s[10:11] offset:160
	global_load_dwordx4 v[186:189], v3, s[10:11] offset:176
	global_load_dwordx4 v[190:193], v3, s[10:11] offset:192
	global_load_dwordx4 v[194:197], v3, s[10:11] offset:208
	global_load_dwordx4 v[198:201], v3, s[10:11] offset:224
	global_load_dwordx4 v[202:205], v3, s[10:11] offset:240
	s_waitcnt vmcnt(0)
; __device__ __forceinline__ float bflo(unsigned w) { return __uint_as_float(w << 16); }
; __device__ __forceinline__ float bfhi(unsigned w) { return __uint_as_float(w & 0xffff0000u); }
; __device__ __forceinline__ unsigned pk2(float lo, float hi) { return pg8::cvt_pk_bf16(lo, hi); }
; __device__ __forceinline__ void norm64_inplace(bf16* p, const float* gain, float mult) {
;     u32x4 w[8]; float ss = 0.f;
; #pragma unroll
;     for (int k = 0; k < 8; ++k) { w[k] = ((const u32x4*)p)[k];
;         const float a0 = bflo(w[k].x), a1 = bfhi(w[k].x), a2 = bflo(w[k].y), a3 = bfhi(w[k].y), a4 = bflo(w[k].z), a5 = bfhi(w[k].z), a6 = bflo(w[k].w), a7 = bfhi(w[k].w);
;         ss += (a0 * a0 + a1 * a1) + (a2 * a2 + a3 * a3) + (a4 * a4 + a5 * a5) + (a6 * a6 + a7 * a7); }
;     const float r = rsqrtf(ss * (1.0f / 64.0f) + EPS) * mult;
; #pragma unroll
;     for (int k = 0; k < 8; ++k) { const f32x4 g0 = *(const f32x4*)(gain + 8 * k), g1 = *(const f32x4*)(gain + 8 * k + 4);
;         u32x4 o; o.x = pk2(bflo(w[k].x) * r * g0[0], bfhi(w[k].x) * r * g0[1]); o.y = pk2(bflo(w[k].y) * r * g0[2], bfhi(w[k].y) * r * g0[3]);
;         o.z = pk2(bflo(w[k].z) * r * g1[0], bfhi(w[k].z) * r * g1[1]); o.w = pk2(bflo(w[k].w) * r * g1[2], bfhi(w[k].w) * r * g1[3]);
;         ((u32x4*)p)[k] = o; }
	v_mov_b64_e32 v[20:21], v[134:135]
	v_mov_b64_e32 v[22:23], v[136:137]
	v_mov_b64_e32 v[24:25], v[130:131]
	v_mov_b64_e32 v[26:27], v[132:133]
	v_and_b32_e32 v13, 0xffff0000, v17
	v_pk_fma_f32 v[72:73], v[46:47], v[46:47], v[2:3] op_sel_hi:[1,1,0]
	v_lshlrev_b32_e32 v12, 16, v17
	v_mul_f32_e32 v2, v13, v13
	v_pk_fma_f32 v[74:75], v[12:13], v[12:13], v[2:3] op_sel_hi:[1,1,0]
	v_mul_f32_e32 v2, v95, v95
	v_pk_fma_f32 v[108:109], v[94:95], v[94:95], v[2:3] op_sel_hi:[1,1,0]
	v_mul_f32_e32 v2, v99, v99
	v_pk_fma_f32 v[16:17], v[98:99], v[98:99], v[2:3] op_sel_hi:[1,1,0]
	v_pk_mov_b32 v[102:103], v[18:19], v[6:7] op_sel:[1,0]
	v_pk_add_f32 v[16:17], v[28:29], v[16:17] op_sel:[1,0] op_sel_hi:[0,1]
	v_pk_add_f32 v[30:31], v[28:29], v[16:17]
	v_pk_mov_b32 v[16:17], v[14:15], v[10:11] op_sel:[1,0]
	v_pk_mul_f32 v[14:15], v[92:93], v[92:93]
	v_and_b32_e32 v91, 0xffff0000, v17
	v_and_b32_e32 v90, 0xffff0000, v16
	v_and_b32_e32 v11, 0xffff0000, v11
	v_and_b32_e32 v10, s0, v10
	v_pk_fma_f32 v[116:117], v[112:113], v[112:113], v[14:15]
	v_pk_mul_f32 v[14:15], v[90:91], v[90:91]
	v_mov_b32_e32 v79, v11
	v_pk_mul_f32 v[10:11], v[10:11], v[10:11]
	v_pk_add_f32 v[30:31], v[108:109], v[30:31]
	v_pk_fma_f32 v[122:123], v[114:115], v[114:115], v[14:15]
	v_mul_f32_e32 v31, v78, v78
	v_mov_b32_e32 v69, v11
	v_pk_add_f32 v[8:9], v[116:117], v[8:9]
	v_pk_add_f32 v[10:11], v[30:31], v[68:69]
	v_pk_add_f32 v[8:9], v[122:123], v[8:9]
	v_lshlrev_b32_e32 v29, 16, v6
	v_pk_add_f32 v[8:9], v[10:11], v[8:9]
	v_lshlrev_b32_e32 v6, 16, v7
	v_pk_add_f32 v[108:109], v[8:9], v[8:9] op_sel:[0,1] op_sel_hi:[1,0]
	v_and_b32_e32 v7, 0xffff0000, v7
	v_pk_add_f32 v[70:71], v[108:109], v[70:71]
	v_lshlrev_b32_e32 v15, 16, v4
	v_and_b32_e32 v17, 0xffff0000, v4
	v_mul_f32_e32 v77, v7, v7
	v_mul_f32_e32 v71, v6, v6
	v_lshlrev_b32_e32 v4, 16, v5
	v_and_b32_e32 v5, 0xffff0000, v5
	v_and_b32_e32 v16, 0xffff0000, v18
	v_pk_add_f32 v[70:71], v[70:71], v[76:77]
	v_pk_mul_f32 v[76:77], v[4:5], v[4:5]
	v_lshlrev_b32_e32 v14, 16, v18
	v_lshlrev_b32_e32 v28, 16, v19
	v_and_b32_e32 v19, 0xffff0000, v103
	v_and_b32_e32 v18, 0xffff0000, v102
	v_pk_mul_f32 v[102:103], v[16:17], v[16:17]
	v_mov_b32_e32 v73, v76
	v_mov_b32_e32 v75, v77
	v_pk_fma_f32 v[124:125], v[14:15], v[14:15], v[102:103]
	v_pk_mul_f32 v[102:103], v[18:19], v[18:19]
	v_pk_add_f32 v[72:73], v[72:73], v[74:75]
	v_pk_fma_f32 v[126:127], v[28:29], v[28:29], v[102:103]
	v_pk_add_f32 v[72:73], v[124:125], v[72:73]
	v_mov_b32_e32 v10, v14
	v_pk_add_f32 v[72:73], v[126:127], v[72:73]
	v_mov_b32_e32 v102, v114
	v_pk_add_f32 v[70:71], v[70:71], v[72:73]
	v_mov_b32_e32 v103, v90
	v_add_f32_e32 v2, v70, v71
	v_fmamk_f32 v2, v2, 0x3c800000, v213
	v_cmp_gt_f32_e32 vcc, s83, v2
	v_mul_f32_e32 v14, 0x4b800000, v2
	v_mov_b32_e32 v92, v113
	v_cndmask_b32_e32 v2, v2, v14, vcc
	v_rsq_f32_e32 v2, v2
	v_mov_b32_e32 v90, v115
	v_mov_b32_e32 v68, v82
	v_mov_b32_e32 v69, v54
	v_mul_f32_e32 v14, 0x45800000, v2
	v_cndmask_b32_e32 v2, v2, v14, vcc
	v_pk_mul_f32 v[70:71], v[2:3], v[100:101] op_sel_hi:[0,1]
	v_pk_mul_f32 v[62:63], v[2:3], v[62:63] op_sel_hi:[0,1]
	v_pk_mul_f32 v[58:59], v[2:3], v[58:59] op_sel_hi:[0,1]
	v_pk_mul_f32 v[56:57], v[2:3], v[56:57] op_sel_hi:[0,1]
	v_mov_b32_e32 v54, v83
	v_pk_mul_f32 v[54:55], v[2:3], v[54:55] op_sel_hi:[0,1]
	v_pk_mul_f32 v[24:25], v[24:25], v[70:71]
	v_pk_mul_f32 v[70:71], v[2:3], v[98:99] op_sel_hi:[0,1]
	v_pk_mul_f32 v[26:27], v[26:27], v[70:71]
	v_cvt_pk_bf16_f32 v24, v24, v25
	v_cvt_pk_bf16_f32 v25, v26, v27
	v_pk_mul_f32 v[26:27], v[2:3], v[96:97] op_sel_hi:[0,1]
	v_pk_mul_f32 v[20:21], v[20:21], v[26:27]
	v_pk_mul_f32 v[70:71], v[2:3], v[110:111] op_sel_hi:[0,1]
	v_cvt_pk_bf16_f32 v26, v20, v21
	v_pk_mul_f32 v[20:21], v[2:3], v[94:95] op_sel_hi:[0,1]
	v_pk_mul_f32 v[20:21], v[22:23], v[20:21]
	v_mov_b32_e32 v66, v84
	v_cvt_pk_bf16_f32 v27, v20, v21
	global_store_dwordx4 v[44:45], v[24:27], off
	v_mov_b64_e32 v[20:21], v[142:143]
	v_mov_b64_e32 v[22:23], v[144:145]
	s_nop 0
	v_mov_b64_e32 v[24:25], v[138:139]
	v_mov_b64_e32 v[26:27], v[140:141]
	v_mov_b32_e32 v67, v52
	v_mov_b32_e32 v52, v85
	v_mov_b32_e32 v64, v86
	v_mov_b32_e32 v65, v50
	v_mov_b32_e32 v50, v87
	v_pk_mul_f32 v[50:51], v[2:3], v[50:51] op_sel_hi:[0,1]
	v_mov_b32_e32 v30, v88
	v_mov_b32_e32 v31, v48
	v_mov_b32_e32 v48, v89
	v_mov_b32_e32 v11, v16
	v_mov_b32_e32 v8, v28
	v_mov_b32_e32 v9, v18
	v_pk_mul_f32 v[12:13], v[2:3], v[12:13] op_sel_hi:[0,1]
	v_pk_mul_f32 v[10:11], v[2:3], v[10:11] op_sel_hi:[0,1]
	v_pk_mul_f32 v[8:9], v[2:3], v[8:9] op_sel_hi:[0,1]
	v_mov_b32_e32 v16, v15
	v_pk_mul_f32 v[4:5], v[2:3], v[4:5] op_sel_hi:[0,1]
	v_mov_b32_e32 v18, v29
	s_mov_b32 s0, s1
	v_pk_mul_f32 v[24:25], v[24:25], v[70:71]
	v_pk_mul_f32 v[26:27], v[26:27], v[62:63]
	v_cvt_pk_bf16_f32 v24, v24, v25
	v_cvt_pk_bf16_f32 v25, v26, v27
	v_pk_mul_f32 v[26:27], v[2:3], v[106:107] op_sel_hi:[0,1]
	v_pk_mul_f32 v[20:21], v[20:21], v[26:27]
	s_nop 0
	v_cvt_pk_bf16_f32 v26, v20, v21
	v_pk_mul_f32 v[20:21], v[2:3], v[60:61] op_sel_hi:[0,1]
	v_pk_mul_f32 v[20:21], v[22:23], v[20:21]
	s_nop 0
	v_cvt_pk_bf16_f32 v27, v20, v21
	global_store_dwordx4 v[44:45], v[24:27], off offset:16
	v_mov_b64_e32 v[20:21], v[150:151]
	v_mov_b64_e32 v[22:23], v[152:153]
	s_nop 0
	v_mov_b64_e32 v[24:25], v[146:147]
	v_mov_b64_e32 v[26:27], v[148:149]
	v_pk_mul_f32 v[24:25], v[24:25], v[58:59]
	v_pk_mul_f32 v[26:27], v[26:27], v[56:57]
	v_cvt_pk_bf16_f32 v24, v24, v25
	v_cvt_pk_bf16_f32 v25, v26, v27
	v_pk_mul_f32 v[26:27], v[2:3], v[104:105] op_sel_hi:[0,1]
	v_pk_mul_f32 v[20:21], v[20:21], v[26:27]
	v_pk_mul_f32 v[56:57], v[2:3], v[92:93] op_sel_hi:[0,1]
	v_cvt_pk_bf16_f32 v26, v20, v21
; #define LAS __attribute__((address_space(3)))
; __device__ __forceinline__ float bflo(unsigned w) { return __uint_as_float(w << 16); }
; __device__ __forceinline__ float bfhi(unsigned w) { return __uint_as_float(w & 0xffff0000u); }
; __device__ __forceinline__ unsigned pk2(float lo, float hi) { return pg8::cvt_pk_bf16(lo, hi); }
; __device__ __forceinline__ void norm64_inplace(bf16* p, const float* gain, float mult) {
;     ...
;     const float r = rsqrtf(ss * (1.0f / 64.0f) + EPS) * mult;
; #pragma unroll
;     for (int k = 0; k < 8; ++k) { const f32x4 g0 = *(const f32x4*)(gain + 8 * k), g1 = *(const f32x4*)(gain + 8 * k + 4);
;         u32x4 o; o.x = pk2(bflo(w[k].x) * r * g0[0], bfhi(w[k].x) * r * g0[1]); o.y = pk2(bflo(w[k].y) * r * g0[2], bfhi(w[k].y) * r * g0[3]);
;         o.z = pk2(bflo(w[k].z) * r * g1[0], bfhi(w[k].z) * r * g1[1]); o.w = pk2(bflo(w[k].w) * r * g1[2], bfhi(w[k].w) * r * g1[3]);
;         ((u32x4*)p)[k] = o; }
; __device__ __forceinline__ void nsa_prep2_phase(bf16* z, const float* qg, const float* kg, bf16* vst, bf16* vwt, LAS unsigned char* lds, int tid, int u0, int ustride) {
;     ...
;         __syncthreads();
;         { const int d = tid >> 3, ch = tid & 7;
; #pragma unroll
;           for (int ti = 0; ti < 8; ++ti) { const int g = ti & 3; bf16* dst = (ti >> 2) ? vwt : vst;
;               const u32x4 w = *(const LAS u32x4*)(lds + ti * TILEB + d * TPITCH + ch * 16);
;               *(u32x4*)(dst + ((size_t)(b * 4 + g) * 64 + d) * SEQ + tb * 64 + ch * 8) = w; } }
;         __syncthreads();
	v_pk_mul_f32 v[20:21], v[2:3], v[102:103] op_sel_hi:[0,1]
	v_pk_mul_f32 v[20:21], v[22:23], v[20:21]
	s_nop 0
	v_cvt_pk_bf16_f32 v27, v20, v21
	global_store_dwordx4 v[44:45], v[24:27], off offset:32
	v_mov_b64_e32 v[20:21], v[158:159]
	v_mov_b64_e32 v[22:23], v[160:161]
	s_nop 0
	v_mov_b64_e32 v[24:25], v[154:155]
	v_mov_b64_e32 v[26:27], v[156:157]
	v_pk_mul_f32 v[24:25], v[24:25], v[56:57]
	v_pk_mul_f32 v[56:57], v[2:3], v[80:81] op_sel_hi:[0,1]
	v_pk_mul_f32 v[26:27], v[26:27], v[56:57]
	v_cvt_pk_bf16_f32 v24, v24, v25
	v_cvt_pk_bf16_f32 v25, v26, v27
	v_pk_mul_f32 v[26:27], v[2:3], v[90:91] op_sel_hi:[0,1]
	v_pk_mul_f32 v[20:21], v[20:21], v[26:27]
	v_pk_mul_f32 v[56:57], v[2:3], v[68:69] op_sel_hi:[0,1]
	v_cvt_pk_bf16_f32 v26, v20, v21
	v_pk_mul_f32 v[20:21], v[2:3], v[78:79] op_sel_hi:[0,1]
	v_pk_mul_f32 v[20:21], v[22:23], v[20:21]
	s_nop 0
	v_cvt_pk_bf16_f32 v27, v20, v21
	global_store_dwordx4 v[44:45], v[24:27], off offset:48
	v_mov_b64_e32 v[20:21], v[166:167]
	v_mov_b64_e32 v[22:23], v[168:169]
	s_nop 0
	v_mov_b64_e32 v[24:25], v[162:163]
	v_mov_b64_e32 v[26:27], v[164:165]
	v_pk_mul_f32 v[24:25], v[24:25], v[56:57]
	v_pk_mul_f32 v[26:27], v[26:27], v[54:55]
	v_cvt_pk_bf16_f32 v24, v24, v25
	v_cvt_pk_bf16_f32 v25, v26, v27
	v_pk_mul_f32 v[26:27], v[2:3], v[66:67] op_sel_hi:[0,1]
	v_pk_mul_f32 v[20:21], v[20:21], v[26:27]
	s_nop 0
	v_cvt_pk_bf16_f32 v26, v20, v21
	v_pk_mul_f32 v[20:21], v[2:3], v[52:53] op_sel_hi:[0,1]
	v_pk_mul_f32 v[20:21], v[22:23], v[20:21]
	v_pk_mul_f32 v[52:53], v[2:3], v[64:65] op_sel_hi:[0,1]
	v_cvt_pk_bf16_f32 v27, v20, v21
	global_store_dwordx4 v[44:45], v[24:27], off offset:64
	v_mov_b64_e32 v[20:21], v[186:187]
	v_mov_b64_e32 v[22:23], v[188:189]
	s_nop 0
	v_mov_b64_e32 v[24:25], v[170:171]
	v_mov_b64_e32 v[26:27], v[172:173]
	v_pk_mul_f32 v[24:25], v[52:53], v[24:25]
	v_pk_mul_f32 v[26:27], v[50:51], v[26:27]
	v_cvt_pk_bf16_f32 v24, v24, v25
	v_cvt_pk_bf16_f32 v25, v26, v27
	v_pk_mul_f32 v[26:27], v[2:3], v[30:31] op_sel_hi:[0,1]
	v_pk_mul_f32 v[20:21], v[26:27], v[20:21]
	v_pk_mul_f32 v[30:31], v[2:3], v[46:47] op_sel_hi:[0,1]
	v_cvt_pk_bf16_f32 v26, v20, v21
	v_pk_mul_f32 v[20:21], v[2:3], v[48:49] op_sel_hi:[0,1]
	v_pk_mul_f32 v[20:21], v[20:21], v[22:23]
	s_nop 0
	v_cvt_pk_bf16_f32 v27, v20, v21
	global_store_dwordx4 v[44:45], v[24:27], off offset:80
	v_mov_b64_e32 v[20:21], v[194:195]
	v_mov_b64_e32 v[22:23], v[196:197]
	s_nop 0
	v_mov_b64_e32 v[24:25], v[190:191]
	v_mov_b64_e32 v[26:27], v[192:193]
	v_pk_mul_f32 v[10:11], v[10:11], v[20:21]
	v_pk_mul_f32 v[24:25], v[30:31], v[24:25]
	v_pk_mul_f32 v[12:13], v[12:13], v[26:27]
	v_pk_mul_f32 v[8:9], v[8:9], v[22:23]
	v_cvt_pk_bf16_f32 v24, v24, v25
	v_cvt_pk_bf16_f32 v25, v12, v13
	v_cvt_pk_bf16_f32 v26, v10, v11
	v_cvt_pk_bf16_f32 v27, v8, v9
	global_store_dwordx4 v[44:45], v[24:27], off offset:96
	v_mov_b64_e32 v[8:9], v[202:203]
	v_mov_b64_e32 v[10:11], v[204:205]
	v_mov_b64_e32 v[20:21], v[198:199]
	v_mov_b64_e32 v[22:23], v[200:201]
	v_pk_mul_f32 v[12:13], v[2:3], v[16:17] op_sel_hi:[0,1]
	v_pk_mul_f32 v[12:13], v[12:13], v[20:21]
	v_pk_mul_f32 v[4:5], v[4:5], v[22:23]
	v_cvt_pk_bf16_f32 v12, v12, v13
	v_cvt_pk_bf16_f32 v13, v4, v5
	v_pk_mul_f32 v[4:5], v[2:3], v[18:19] op_sel_hi:[0,1]
	v_pk_mul_f32 v[4:5], v[4:5], v[8:9]
	v_lshl_add_u64 v[8:9], v[36:37], 0, s[6:7]
	v_cvt_pk_bf16_f32 v14, v4, v5
	v_pk_mul_f32 v[4:5], v[2:3], v[6:7] op_sel_hi:[0,1]
	v_pk_mul_f32 v[4:5], v[4:5], v[10:11]
	v_lshl_add_u64 v[8:9], v[8:9], 0, s[68:69]
	v_cvt_pk_bf16_f32 v15, v4, v5
	global_store_dwordx4 v[44:45], v[12:15], off offset:112
	s_waitcnt lgkmcnt(0)
	s_barrier
	ds_read_b128 v[4:7], v120
	v_lshl_add_u64 v[8:9], v[8:9], 0, v[42:43]
	s_waitcnt lgkmcnt(0)
	global_store_dwordx4 v[8:9], v[4:7], off
	ds_read_b128 v[4:7], v120 offset:9216
	v_lshl_add_u64 v[8:9], v[36:37], 0, s[16:17]
	v_lshl_add_u64 v[8:9], v[8:9], 0, s[68:69]
	v_lshl_add_u64 v[8:9], v[8:9], 0, v[42:43]
	s_waitcnt lgkmcnt(0)
	global_store_dwordx4 v[8:9], v[4:7], off
	ds_read_b128 v[4:7], v120 offset:18432
	v_lshl_add_u64 v[8:9], v[36:37], 0, s[18:19]
	v_lshl_add_u64 v[8:9], v[8:9], 0, s[68:69]
	v_lshl_add_u64 v[8:9], v[8:9], 0, v[42:43]
	s_waitcnt lgkmcnt(0)
	global_store_dwordx4 v[8:9], v[4:7], off
	ds_read_b128 v[4:7], v120 offset:27648
	v_lshl_add_u64 v[8:9], v[36:37], 0, s[4:5]
	v_lshl_add_u64 v[8:9], v[8:9], 0, s[68:69]
	v_lshl_add_u64 v[8:9], v[8:9], 0, v[42:43]
	s_waitcnt lgkmcnt(0)
	global_store_dwordx4 v[8:9], v[4:7], off
	ds_read_b128 v[4:7], v120 offset:36864
	v_lshl_add_u64 v[8:9], v[38:39], 0, s[6:7]
	v_lshl_add_u64 v[8:9], v[8:9], 0, s[68:69]
	v_lshl_add_u64 v[8:9], v[8:9], 0, v[42:43]
	s_waitcnt lgkmcnt(0)
	global_store_dwordx4 v[8:9], v[4:7], off
	ds_read_b128 v[4:7], v120 offset:46080
	v_lshl_add_u64 v[8:9], v[38:39], 0, s[16:17]
	v_lshl_add_u64 v[8:9], v[8:9], 0, s[68:69]
	v_lshl_add_u64 v[8:9], v[8:9], 0, v[42:43]
	s_waitcnt lgkmcnt(0)
	global_store_dwordx4 v[8:9], v[4:7], off
	ds_read_b128 v[4:7], v120 offset:55296
	v_lshl_add_u64 v[8:9], v[38:39], 0, s[18:19]
	v_lshl_add_u64 v[8:9], v[8:9], 0, s[68:69]
	v_lshl_add_u64 v[8:9], v[8:9], 0, v[42:43]
	s_waitcnt lgkmcnt(0)
	global_store_dwordx4 v[8:9], v[4:7], off
	ds_read_b128 v[4:7], v120 offset:64512
	v_lshl_add_u64 v[8:9], v[38:39], 0, s[4:5]
	v_lshl_add_u64 v[8:9], v[8:9], 0, s[68:69]
	v_lshl_add_u64 v[8:9], v[8:9], 0, v[42:43]
	s_waitcnt lgkmcnt(0)
	global_store_dwordx4 v[8:9], v[4:7], off
	s_barrier
	s_cbranch_scc1 .LBB0_691
; #define LAS __attribute__((address_space(3)))
; __device__ __forceinline__ float bflo(unsigned w) { return __uint_as_float(w << 16); }
; __device__ __forceinline__ float bfhi(unsigned w) { return __uint_as_float(w & 0xffff0000u); }
; __device__ __forceinline__ int vpos(int k) { return (k & ~12) | ((k & 4) << 1) | ((k & 8) >> 1); }
; __device__ __forceinline__ void norm64_inplace(bf16* p, const float* gain, float mult) {
;     ...
;     for (int k = 0; k < 8; ++k) { w[k] = ((const u32x4*)p)[k];
;         const float a0 = bflo(w[k].x), a1 = bfhi(w[k].x), a2 = bflo(w[k].y), a3 = bfhi(w[k].y), a4 = bflo(w[k].z), a5 = bfhi(w[k].z), a6 = bflo(w[k].w), a7 = bfhi(w[k].w);
;         ss += (a0 * a0 + a1 * a1) + (a2 * a2 + a3 * a3) + (a4 * a4 + a5 * a5) + (a6 * a6 + a7 * a7); }
; __device__ __forceinline__ void nsa_prep2_phase(bf16* z, const float* qg, const float* kg, bf16* vst, bf16* vwt, LAS unsigned char* lds, int tid, int u0, int ustride) {
;     ...
;         { const int tok = tid >> 3, ch = tid & 7, pc = vpos(tok);
; #pragma unroll
;           for (int ti = 0; ti < 8; ++ti) { const int g = ti & 3, col = ((ti >> 2) ? C_VW : C_VS) + g * 64 + ch * 8;
;               const u32x4 w = *(const u32x4*)(z + (row0 + tok) * ZP + col);
;               LAS unsigned short* T = (LAS unsigned short*)(lds + ti * TILEB) + pc;
;               T[(ch * 8 + 0) * 72] = (unsigned short)(w.x & 0xffffu); T[(ch * 8 + 1) * 72] = (unsigned short)(w.x >> 16);
;               T[(ch * 8 + 2) * 72] = (unsigned short)(w.y & 0xffffu); T[(ch * 8 + 3) * 72] = (unsigned short)(w.y >> 16);
;               T[(ch * 8 + 4) * 72] = (unsigned short)(w.z & 0xffffu); T[(ch * 8 + 5) * 72] = (unsigned short)(w.z >> 16);
;               T[(ch * 8 + 6) * 72] = (unsigned short)(w.w & 0xffffu); T[(ch * 8 + 7) * 72] = (unsigned short)(w.w >> 16); } }
; #pragma unroll 1
;         for (int v = tid; v < 1024; v += 512) { const int tok = v >> 4, hd = v & 15; norm64_inplace(z + (row0 + tok) * ZP + C_NQ + hd * 64, qg, 0.125f * LOG2E); }
.LBB0_688:
	s_ashr_i32 s16, s0, 5
	s_ashr_i32 s17, s16, 31
	s_lshl_b32 s1, s0, 6
	s_lshl_b64 s[18:19], s[16:17], 11
	s_and_b32 s1, s1, 0x7c0
	s_or_b32 s18, s18, s1
	v_lshl_add_u64 v[30:31], s[18:19], 0, v[32:33]
	v_mad_u64_u32 v[4:5], s[4:5], v30, s88, v[40:41]
	s_movk_i32 s4, 0x2000
	v_mad_i32_i24 v2, v31, s88, v5
	v_add_co_u32_e32 v4, vcc, s4, v4
	s_nop 1
	v_addc_co_u32_e32 v5, vcc, 0, v2, vcc
	global_load_dwordx4 v[6:9], v[4:5], off offset:512
	global_load_dwordx4 v[10:13], v[4:5], off offset:640
	global_load_dwordx4 v[14:17], v[4:5], off offset:768
	global_load_dwordx4 v[18:21], v[4:5], off offset:896
	global_load_dwordx4 v[22:25], v[4:5], off offset:1536
	global_load_dwordx4 v[26:29], v[4:5], off offset:1664
	s_waitcnt vmcnt(5)
	ds_write_b16 v118, v6
	ds_write_b16_d16_hi v118, v6 offset:144
	ds_write_b16 v118, v7 offset:288
	ds_write_b16_d16_hi v118, v7 offset:432
	ds_write_b16 v118, v8 offset:576
	ds_write_b16_d16_hi v118, v8 offset:720
	ds_write_b16 v118, v9 offset:864
	ds_write_b16_d16_hi v118, v9 offset:1008
	global_load_dwordx4 v[6:9], v[4:5], off offset:1792
	s_waitcnt vmcnt(5)
	ds_write_b16 v118, v10 offset:9216
	ds_write_b16_d16_hi v118, v10 offset:9360
	ds_write_b16 v118, v11 offset:9504
	ds_write_b16_d16_hi v118, v11 offset:9648
	ds_write_b16 v118, v12 offset:9792
	ds_write_b16_d16_hi v118, v12 offset:9936
	ds_write_b16 v118, v13 offset:10080
	ds_write_b16_d16_hi v118, v13 offset:10224
	global_load_dwordx4 v[10:13], v[4:5], off offset:1920
	s_waitcnt vmcnt(5)
	ds_write_b16 v118, v14 offset:18432
	ds_write_b16_d16_hi v118, v14 offset:18576
	ds_write_b16 v118, v15 offset:18720
	ds_write_b16_d16_hi v118, v15 offset:18864
	ds_write_b16 v118, v16 offset:19008
	ds_write_b16_d16_hi v118, v16 offset:19152
	ds_write_b16 v118, v17 offset:19296
	ds_write_b16_d16_hi v118, v17 offset:19440
	s_waitcnt vmcnt(4)
	ds_write_b16 v118, v18 offset:27648
	ds_write_b16_d16_hi v118, v18 offset:27792
	ds_write_b16 v118, v19 offset:27936
	ds_write_b16_d16_hi v118, v19 offset:28080
	ds_write_b16 v118, v20 offset:28224
	ds_write_b16_d16_hi v118, v20 offset:28368
	ds_write_b16 v118, v21 offset:28512
	ds_write_b16_d16_hi v118, v21 offset:28656
	s_waitcnt vmcnt(3)
	ds_write_b16 v118, v22 offset:36864
	ds_write_b16_d16_hi v118, v22 offset:37008
	ds_write_b16 v118, v23 offset:37152
	ds_write_b16_d16_hi v118, v23 offset:37296
	ds_write_b16 v118, v24 offset:37440
	ds_write_b16_d16_hi v118, v24 offset:37584
	ds_write_b16 v118, v25 offset:37728
	ds_write_b16_d16_hi v118, v25 offset:37872
	s_waitcnt vmcnt(2)
	ds_write_b16 v118, v26 offset:46080
	ds_write_b16_d16_hi v118, v26 offset:46224
	ds_write_b16 v118, v27 offset:46368
	ds_write_b16_d16_hi v118, v27 offset:46512
	ds_write_b16 v118, v28 offset:46656
	ds_write_b16_d16_hi v118, v28 offset:46800
	ds_write_b16 v118, v29 offset:46944
	ds_write_b16_d16_hi v118, v29 offset:47088
	s_waitcnt vmcnt(1)
	ds_write_b16 v118, v6 offset:55296
	ds_write_b16_d16_hi v118, v6 offset:55440
	ds_write_b16 v118, v7 offset:55584
	ds_write_b16_d16_hi v118, v7 offset:55728
	ds_write_b16 v118, v8 offset:55872
	ds_write_b16_d16_hi v118, v8 offset:56016
	ds_write_b16 v118, v9 offset:56160
	ds_write_b16_d16_hi v118, v9 offset:56304
	s_waitcnt vmcnt(0)
	ds_write_b16 v118, v10 offset:64512
	ds_write_b16_d16_hi v118, v10 offset:64656
	ds_write_b16 v118, v11 offset:64800
	ds_write_b16_d16_hi v118, v11 offset:64944
	ds_write_b16 v118, v12 offset:65088
	ds_write_b16_d16_hi v118, v12 offset:65232
	ds_write_b16 v118, v13 offset:65376
	ds_write_b16_d16_hi v118, v13 offset:65520
	s_and_saveexec_b64 s[20:21], s[8:9]
	s_cbranch_execz .LBB0_687
	s_mov_b64 s[22:23], 0
	v_mov_b32_e32 v43, v119
	v_mov_b32_e32 v121, v1
.LBB0_690:
	v_ashrrev_i32_e32 v4, 4, v121
	v_ashrrev_i32_e32 v5, 31, v4
	v_lshl_add_u64 v[4:5], s[18:19], 0, v[4:5]
	v_mov_b64_e32 v[6:7], s[76:77]
	v_mad_u64_u32 v[6:7], s[4:5], v4, s88, v[6:7]
	v_mov_b32_e32 v2, v7
	v_mad_u64_u32 v[4:5], s[4:5], v5, s88, v[2:3]
	v_and_b32_e32 v2, 0x3c0, v43
	v_mov_b32_e32 v7, v4
	v_lshlrev_b32_e32 v2, 1, v2
	v_lshl_add_u64 v[4:5], v[6:7], 0, v[2:3]
	v_add_co_u32_e32 v64, vcc, s75, v4
	v_lshl_add_u64 v[44:45], v[4:5], 0, s[66:67]
	s_nop 0
	v_addc_co_u32_e32 v65, vcc, 0, v5, vcc
	global_load_dwordx4 v[26:29], v[64:65], off offset:1024
	global_load_dwordx4 v[16:19], v[44:45], off offset:48
	global_load_dwordx4 v[22:25], v[44:45], off offset:32
	global_load_dwordx4 v[4:7], v[44:45], off offset:16
	v_add_u32_e32 v43, 0x8000, v43
	s_waitcnt vmcnt(3)
	v_and_b32_e32 v83, 0xffff0000, v29
	v_and_b32_e32 v87, 0xffff0000, v28
	s_waitcnt vmcnt(1)
	v_lshlrev_b32_e32 v58, 16, v22
	s_waitcnt vmcnt(0)
	v_and_b32_e32 v63, 0xffff0000, v5
	v_and_b32_e32 v62, 0xffff0000, v4
	v_lshlrev_b32_e32 v101, 16, v5
	v_lshlrev_b32_e32 v100, 16, v4
	v_pk_mul_f32 v[4:5], v[62:63], v[62:63]
	v_and_b32_e32 v61, 0xffff0000, v7
	v_and_b32_e32 v60, 0xffff0000, v6
	v_pk_fma_f32 v[4:5], v[100:101], v[100:101], v[4:5]
	v_lshlrev_b32_e32 v103, 16, v7
	v_lshlrev_b32_e32 v102, 16, v6
	v_pk_mul_f32 v[6:7], v[60:61], v[60:61]
	v_pk_add_f32 v[4:5], v[4:5], v[4:5] op_sel:[0,1] op_sel_hi:[1,0]
	v_pk_fma_f32 v[6:7], v[102:103], v[102:103], v[6:7]
	v_and_b32_e32 v59, 0xffff0000, v22
	v_pk_add_f32 v[4:5], v[6:7], v[4:5]
	v_lshlrev_b32_e32 v56, 16, v23
	v_pk_add_f32 v[92:93], v[6:7], v[4:5] op_sel:[1,0] op_sel_hi:[0,1]
	v_and_b32_e32 v57, 0xffff0000, v23
	global_load_dwordx4 v[4:7], v[44:45], off offset:112
	global_load_dwordx4 v[20:23], v[44:45], off offset:96
	global_load_dwordx4 v[8:11], v[44:45], off offset:80
	global_load_dwordx4 v[12:15], v[44:45], off offset:64
	v_mul_f32_e32 v2, v59, v59
	v_pk_fma_f32 v[72:73], v[58:59], v[58:59], v[2:3] op_sel_hi:[1,1,0]
	v_mul_f32_e32 v2, v57, v57
	v_pk_fma_f32 v[84:85], v[56:57], v[56:57], v[2:3] op_sel_hi:[1,1,0]
	v_and_b32_e32 v99, 0xffff0000, v26
	v_lshlrev_b32_e32 v82, 16, v29
	v_lshlrev_b32_e32 v86, 16, v28
	v_and_b32_e32 v89, 0xffff0000, v27
	v_lshlrev_b32_e32 v98, 16, v26
	v_mov_b32_e32 v76, v87
	v_mov_b32_e32 v77, v99
	v_lshlrev_b32_e32 v88, 16, v27
	v_mov_b32_e32 v26, v86
	v_mov_b32_e32 v27, v98
	v_pk_mul_f32 v[76:77], v[76:77], v[76:77]
	v_lshlrev_b32_e32 v125, 16, v18
	v_pk_fma_f32 v[26:27], v[26:27], v[26:27], v[76:77]
	v_mov_b32_e32 v110, v100
	v_lshlrev_b32_e32 v100, 16, v19
	v_mov_b32_e32 v111, v62
	v_mov_b32_e32 v62, v101
	v_lshlrev_b32_e32 v123, 16, v16
	v_and_b32_e32 v81, 0xffff0000, v16
	v_and_b32_e32 v80, 0xffff0000, v24
	v_lshlrev_b32_e32 v122, 16, v24
	v_lshlrev_b32_e32 v124, 16, v25
	v_mov_b32_e32 v108, v102
	v_mov_b32_e32 v109, v60
	v_mov_b32_e32 v60, v103
	v_mov_b32_e32 v102, v124
	s_waitcnt vmcnt(2)
; __device__ __forceinline__ float bflo(unsigned w) { return __uint_as_float(w << 16); }
; __device__ __forceinline__ float bfhi(unsigned w) { return __uint_as_float(w & 0xffff0000u); }
; __device__ __forceinline__ void norm64_inplace(bf16* p, const float* gain, float mult) {
;     u32x4 w[8]; float ss = 0.f;
; #pragma unroll
;     for (int k = 0; k < 8; ++k) { w[k] = ((const u32x4*)p)[k];
;         const float a0 = bflo(w[k].x), a1 = bfhi(w[k].x), a2 = bflo(w[k].y), a3 = bfhi(w[k].y), a4 = bflo(w[k].z), a5 = bfhi(w[k].z), a6 = bflo(w[k].w), a7 = bfhi(w[k].w);
;         ss += (a0 * a0 + a1 * a1) + (a2 * a2 + a3 * a3) + (a4 * a4 + a5 * a5) + (a6 * a6 + a7 * a7); }
;     const float r = rsqrtf(ss * (1.0f / 64.0f) + EPS) * mult;
; #pragma unroll
;     for (int k = 0; k < 8; ++k) { const f32x4 g0 = *(const f32x4*)(gain + 8 * k), g1 = *(const f32x4*)(gain + 8 * k + 4);
	v_and_b32_e32 v47, 0xffff0000, v20
	s_waitcnt vmcnt(1)
	v_and_b32_e32 v51, 0xffff0000, v9
	s_waitcnt vmcnt(0)
	v_and_b32_e32 v55, 0xffff0000, v13
	v_and_b32_e32 v54, 0xffff0000, v12
	v_and_b32_e32 v50, 0xffff0000, v8
	v_lshlrev_b32_e32 v79, 16, v13
	v_lshlrev_b32_e32 v78, 16, v12
	v_pk_mul_f32 v[12:13], v[54:55], v[54:55]
	v_and_b32_e32 v53, 0xffff0000, v15
	v_and_b32_e32 v52, 0xffff0000, v14
	v_lshlrev_b32_e32 v95, 16, v9
	v_lshlrev_b32_e32 v94, 16, v8
	v_pk_mul_f32 v[8:9], v[50:51], v[50:51]
	v_and_b32_e32 v49, 0xffff0000, v11
	v_and_b32_e32 v48, 0xffff0000, v10
	v_pk_fma_f32 v[12:13], v[78:79], v[78:79], v[12:13]
	v_lshlrev_b32_e32 v91, 16, v15
	v_lshlrev_b32_e32 v90, 16, v14
	v_pk_mul_f32 v[14:15], v[52:53], v[52:53]
	v_pk_fma_f32 v[8:9], v[94:95], v[94:95], v[8:9]
	v_lshlrev_b32_e32 v97, 16, v11
	v_lshlrev_b32_e32 v96, 16, v10
	v_pk_mul_f32 v[10:11], v[48:49], v[48:49]
	v_pk_add_f32 v[12:13], v[12:13], v[12:13] op_sel:[0,1] op_sel_hi:[1,0]
	v_pk_fma_f32 v[14:15], v[90:91], v[90:91], v[14:15]
	v_pk_add_f32 v[8:9], v[8:9], v[8:9] op_sel:[0,1] op_sel_hi:[1,0]
	v_pk_fma_f32 v[10:11], v[96:97], v[96:97], v[10:11]
	v_pk_add_f32 v[12:13], v[14:15], v[12:13]
	v_pk_add_f32 v[8:9], v[10:11], v[8:9]
	v_pk_add_f32 v[70:71], v[14:15], v[12:13] op_sel:[1,0] op_sel_hi:[0,1]
	v_pk_add_f32 v[74:75], v[10:11], v[8:9] op_sel:[1,0] op_sel_hi:[0,1]
	global_load_dwordx4 v[130:133], v3, s[14:15]
	global_load_dwordx4 v[134:137], v3, s[14:15] offset:16
	global_load_dwordx4 v[138:141], v3, s[14:15] offset:32
	global_load_dwordx4 v[142:145], v3, s[14:15] offset:48
	global_load_dwordx4 v[146:149], v3, s[14:15] offset:64
	global_load_dwordx4 v[150:153], v3, s[14:15] offset:80
	global_load_dwordx4 v[154:157], v3, s[14:15] offset:96
	global_load_dwordx4 v[158:161], v3, s[14:15] offset:112
	global_load_dwordx4 v[162:165], v3, s[14:15] offset:128
	global_load_dwordx4 v[166:169], v3, s[14:15] offset:144
	global_load_dwordx4 v[170:173], v3, s[14:15] offset:160
	global_load_dwordx4 v[186:189], v3, s[14:15] offset:176
	global_load_dwordx4 v[190:193], v3, s[14:15] offset:192
	global_load_dwordx4 v[194:197], v3, s[14:15] offset:208
	global_load_dwordx4 v[198:201], v3, s[14:15] offset:224
	global_load_dwordx4 v[202:205], v3, s[14:15] offset:240
	s_waitcnt vmcnt(0)
	v_mov_b64_e32 v[8:9], v[134:135]
	v_mov_b64_e32 v[10:11], v[136:137]
	v_mov_b64_e32 v[12:13], v[130:131]
	v_mov_b64_e32 v[14:15], v[132:133]
	v_lshlrev_b32_e32 v46, 16, v20
	v_mul_f32_e32 v2, v47, v47
	v_lshlrev_b32_e32 v20, 16, v21
	v_and_b32_e32 v21, 0xffff0000, v21
	v_pk_fma_f32 v[66:67], v[46:47], v[46:47], v[2:3] op_sel_hi:[1,1,0]
	v_mul_f32_e32 v2, v21, v21
	v_pk_fma_f32 v[68:69], v[20:21], v[20:21], v[2:3] op_sel_hi:[1,1,0]
	v_mul_f32_e32 v2, v83, v83
	v_pk_fma_f32 v[106:107], v[82:83], v[82:83], v[2:3] op_sel_hi:[1,1,0]
	v_mul_f32_e32 v2, v89, v89
	v_pk_fma_f32 v[28:29], v[88:89], v[88:89], v[2:3] op_sel_hi:[1,1,0]
	v_pk_mov_b32 v[104:105], v[22:23], v[6:7] op_sel:[1,0]
	v_pk_add_f32 v[28:29], v[26:27], v[28:29] op_sel:[1,0] op_sel_hi:[0,1]
	v_pk_add_f32 v[116:117], v[26:27], v[28:29]
	v_pk_mov_b32 v[26:27], v[24:25], v[18:19] op_sel:[1,0]
	v_and_b32_e32 v19, 0xffff0000, v19
	v_and_b32_e32 v18, s0, v18
	v_mov_b32_e32 v101, v19
	v_pk_mul_f32 v[18:19], v[18:19], v[18:19]
	v_pk_add_f32 v[106:107], v[106:107], v[116:117]
	v_mov_b32_e32 v93, v19
	v_mul_f32_e32 v107, v100, v100
	v_pk_add_f32 v[18:19], v[106:107], v[92:93]
	v_lshlrev_b32_e32 v106, 16, v17
	v_and_b32_e32 v107, 0xffff0000, v17
	v_pk_mul_f32 v[16:17], v[106:107], v[106:107]
	v_and_b32_e32 v77, 0xffff0000, v27
	v_and_b32_e32 v76, 0xffff0000, v26
	v_pk_mul_f32 v[24:25], v[80:81], v[80:81]
	v_mov_b32_e32 v73, v16
	v_mov_b32_e32 v85, v17
	v_pk_fma_f32 v[126:127], v[122:123], v[122:123], v[24:25]
	v_pk_mul_f32 v[24:25], v[76:77], v[76:77]
	v_pk_add_f32 v[16:17], v[72:73], v[84:85]
	v_pk_fma_f32 v[128:129], v[124:125], v[124:125], v[24:25]
	v_pk_add_f32 v[16:17], v[126:127], v[16:17]
	v_lshlrev_b32_e32 v29, 16, v6
	v_pk_add_f32 v[16:17], v[128:129], v[16:17]
	v_lshlrev_b32_e32 v6, 16, v7
	v_pk_add_f32 v[16:17], v[18:19], v[16:17]
	v_and_b32_e32 v7, 0xffff0000, v7
	v_pk_add_f32 v[116:117], v[16:17], v[16:17] op_sel:[0,1] op_sel_hi:[1,0]
	v_lshlrev_b32_e32 v25, 16, v4
	v_pk_add_f32 v[70:71], v[116:117], v[70:71]
	v_and_b32_e32 v27, 0xffff0000, v4
	v_mul_f32_e32 v75, v7, v7
	v_mul_f32_e32 v71, v6, v6
	v_lshlrev_b32_e32 v4, 16, v5
	v_and_b32_e32 v5, 0xffff0000, v5
	v_and_b32_e32 v26, 0xffff0000, v22
	v_pk_add_f32 v[70:71], v[70:71], v[74:75]
	v_pk_mul_f32 v[74:75], v[4:5], v[4:5]
	v_lshlrev_b32_e32 v24, 16, v22
	v_lshlrev_b32_e32 v28, 16, v23
	v_and_b32_e32 v23, 0xffff0000, v105
	v_and_b32_e32 v22, 0xffff0000, v104
	v_pk_mul_f32 v[104:105], v[26:27], v[26:27]
	v_mov_b32_e32 v67, v74
	v_mov_b32_e32 v69, v75
	v_pk_fma_f32 v[114:115], v[24:25], v[24:25], v[104:105]
	v_pk_mul_f32 v[104:105], v[22:23], v[22:23]
	v_pk_add_f32 v[66:67], v[66:67], v[68:69]
	v_pk_fma_f32 v[112:113], v[28:29], v[28:29], v[104:105]
	v_pk_add_f32 v[66:67], v[114:115], v[66:67]
	v_mov_b32_e32 v17, v22
	v_pk_add_f32 v[66:67], v[112:113], v[66:67]
	v_mov_b32_e32 v104, v122
	v_pk_add_f32 v[66:67], v[70:71], v[66:67]
	v_mov_b32_e32 v105, v80
	v_add_f32_e32 v2, v66, v67
	v_fmamk_f32 v2, v2, 0x3c800000, v213
	v_cmp_gt_f32_e32 vcc, s83, v2
	v_mul_f32_e32 v22, 0x4b800000, v2
	v_mov_b32_e32 v103, v76
	v_cndmask_b32_e32 v2, v2, v22, vcc
	v_rsq_f32_e32 v2, v2
	v_mov_b32_e32 v80, v123
	v_mov_b32_e32 v76, v125
	v_mov_b32_e32 v92, v78
	v_mul_f32_e32 v22, 0x45800000, v2
	v_cndmask_b32_e32 v2, v2, v22, vcc
	v_mul_f32_e32 v2, 0x3e38aa3b, v2
	v_pk_mul_f32 v[66:67], v[2:3], v[98:99] op_sel_hi:[0,1]
; __device__ __forceinline__ float bflo(unsigned w) { return __uint_as_float(w << 16); }
; __device__ __forceinline__ float bfhi(unsigned w) { return __uint_as_float(w & 0xffff0000u); }
; __device__ __forceinline__ unsigned pk2(float lo, float hi) { return pg8::cvt_pk_bf16(lo, hi); }
; __device__ __forceinline__ void norm64_inplace(bf16* p, const float* gain, float mult) {
;     ...
; #pragma unroll
;     for (int k = 0; k < 8; ++k) { const f32x4 g0 = *(const f32x4*)(gain + 8 * k), g1 = *(const f32x4*)(gain + 8 * k + 4);
;         u32x4 o; o.x = pk2(bflo(w[k].x) * r * g0[0], bfhi(w[k].x) * r * g0[1]); o.y = pk2(bflo(w[k].y) * r * g0[2], bfhi(w[k].y) * r * g0[3]);
;         o.z = pk2(bflo(w[k].z) * r * g1[0], bfhi(w[k].z) * r * g1[1]); o.w = pk2(bflo(w[k].w) * r * g1[2], bfhi(w[k].w) * r * g1[3]);
;         ((u32x4*)p)[k] = o; }
	v_pk_mul_f32 v[12:13], v[12:13], v[66:67]
	v_pk_mul_f32 v[66:67], v[2:3], v[88:89] op_sel_hi:[0,1]
	v_pk_mul_f32 v[14:15], v[14:15], v[66:67]
	v_cvt_pk_bf16_f32 v12, v12, v13
	v_cvt_pk_bf16_f32 v13, v14, v15
	v_pk_mul_f32 v[14:15], v[2:3], v[86:87] op_sel_hi:[0,1]
	v_pk_mul_f32 v[8:9], v[8:9], v[14:15]
	v_pk_mul_f32 v[62:63], v[2:3], v[62:63] op_sel_hi:[0,1]
	v_cvt_pk_bf16_f32 v14, v8, v9
	v_pk_mul_f32 v[8:9], v[2:3], v[82:83] op_sel_hi:[0,1]
	v_pk_mul_f32 v[8:9], v[10:11], v[8:9]
	v_pk_mul_f32 v[58:59], v[2:3], v[58:59] op_sel_hi:[0,1]
	v_cvt_pk_bf16_f32 v15, v8, v9
	global_store_dwordx4 v[64:65], v[12:15], off offset:1024
	v_mov_b64_e32 v[8:9], v[142:143]
	v_mov_b64_e32 v[10:11], v[144:145]
	s_nop 0
	v_mov_b64_e32 v[12:13], v[138:139]
	v_mov_b64_e32 v[14:15], v[140:141]
	v_pk_mul_f32 v[64:65], v[2:3], v[110:111] op_sel_hi:[0,1]
	v_pk_mul_f32 v[56:57], v[2:3], v[56:57] op_sel_hi:[0,1]
	v_mov_b32_e32 v93, v54
	v_mov_b32_e32 v54, v79
	v_pk_mul_f32 v[54:55], v[2:3], v[54:55] op_sel_hi:[0,1]
	v_mov_b32_e32 v84, v90
	v_mov_b32_e32 v85, v52
	v_mov_b32_e32 v52, v91
	v_mov_b32_e32 v78, v94
	v_mov_b32_e32 v79, v50
	v_mov_b32_e32 v50, v95
	v_pk_mul_f32 v[50:51], v[2:3], v[50:51] op_sel_hi:[0,1]
	v_mov_b32_e32 v72, v96
	v_mov_b32_e32 v73, v48
	v_mov_b32_e32 v48, v97
	v_pk_mul_f32 v[46:47], v[2:3], v[46:47] op_sel_hi:[0,1]
	v_pk_mul_f32 v[20:21], v[2:3], v[20:21] op_sel_hi:[0,1]
	v_mov_b32_e32 v18, v24
	v_mov_b32_e32 v19, v26
	v_mov_b32_e32 v16, v28
	v_mov_b32_e32 v26, v25
	v_pk_mul_f32 v[4:5], v[2:3], v[4:5] op_sel_hi:[0,1]
	v_mov_b32_e32 v22, v29
	v_cmp_lt_i32_e32 vcc, s93, v121
	s_or_b64 s[22:23], vcc, s[22:23]
	v_pk_mul_f32 v[12:13], v[12:13], v[64:65]
	v_pk_mul_f32 v[14:15], v[14:15], v[62:63]
	v_cvt_pk_bf16_f32 v12, v12, v13
	v_cvt_pk_bf16_f32 v13, v14, v15
	v_pk_mul_f32 v[14:15], v[2:3], v[108:109] op_sel_hi:[0,1]
	v_pk_mul_f32 v[8:9], v[8:9], v[14:15]
	s_nop 0
	v_cvt_pk_bf16_f32 v14, v8, v9
	v_pk_mul_f32 v[8:9], v[2:3], v[60:61] op_sel_hi:[0,1]
	v_pk_mul_f32 v[8:9], v[10:11], v[8:9]
	s_nop 0
	v_cvt_pk_bf16_f32 v15, v8, v9
	global_store_dwordx4 v[44:45], v[12:15], off offset:16
	v_mov_b64_e32 v[8:9], v[150:151]
	v_mov_b64_e32 v[10:11], v[152:153]
	s_nop 0
	v_mov_b64_e32 v[12:13], v[146:147]
	v_mov_b64_e32 v[14:15], v[148:149]
	v_pk_mul_f32 v[12:13], v[12:13], v[58:59]
	v_pk_mul_f32 v[14:15], v[14:15], v[56:57]
	v_cvt_pk_bf16_f32 v12, v12, v13
	v_cvt_pk_bf16_f32 v13, v14, v15
	v_pk_mul_f32 v[14:15], v[2:3], v[104:105] op_sel_hi:[0,1]
	v_pk_mul_f32 v[8:9], v[8:9], v[14:15]
	v_pk_mul_f32 v[56:57], v[2:3], v[80:81] op_sel_hi:[0,1]
	v_cvt_pk_bf16_f32 v14, v8, v9
	v_pk_mul_f32 v[8:9], v[2:3], v[102:103] op_sel_hi:[0,1]
	v_pk_mul_f32 v[8:9], v[10:11], v[8:9]
	s_nop 0
	v_cvt_pk_bf16_f32 v15, v8, v9
	global_store_dwordx4 v[44:45], v[12:15], off offset:32
	v_mov_b64_e32 v[8:9], v[158:159]
	v_mov_b64_e32 v[10:11], v[160:161]
	s_nop 0
	v_mov_b64_e32 v[12:13], v[154:155]
	v_mov_b64_e32 v[14:15], v[156:157]
	v_pk_mul_f32 v[12:13], v[12:13], v[56:57]
	v_pk_mul_f32 v[56:57], v[2:3], v[106:107] op_sel_hi:[0,1]
	v_pk_mul_f32 v[14:15], v[14:15], v[56:57]
	v_cvt_pk_bf16_f32 v12, v12, v13
	v_cvt_pk_bf16_f32 v13, v14, v15
	v_pk_mul_f32 v[14:15], v[2:3], v[76:77] op_sel_hi:[0,1]
	v_pk_mul_f32 v[8:9], v[8:9], v[14:15]
	v_pk_mul_f32 v[56:57], v[2:3], v[92:93] op_sel_hi:[0,1]
	v_cvt_pk_bf16_f32 v14, v8, v9
	v_pk_mul_f32 v[8:9], v[2:3], v[100:101] op_sel_hi:[0,1]
	v_pk_mul_f32 v[8:9], v[10:11], v[8:9]
	s_nop 0
	v_cvt_pk_bf16_f32 v15, v8, v9
	global_store_dwordx4 v[44:45], v[12:15], off offset:48
	v_mov_b64_e32 v[8:9], v[166:167]
	v_mov_b64_e32 v[10:11], v[168:169]
	s_nop 0
	v_mov_b64_e32 v[12:13], v[162:163]
	v_mov_b64_e32 v[14:15], v[164:165]
	v_pk_mul_f32 v[12:13], v[12:13], v[56:57]
	v_pk_mul_f32 v[14:15], v[14:15], v[54:55]
	v_cvt_pk_bf16_f32 v12, v12, v13
	v_cvt_pk_bf16_f32 v13, v14, v15
	v_pk_mul_f32 v[14:15], v[2:3], v[84:85] op_sel_hi:[0,1]
	v_pk_mul_f32 v[8:9], v[8:9], v[14:15]
	s_nop 0
	v_cvt_pk_bf16_f32 v14, v8, v9
	v_pk_mul_f32 v[8:9], v[2:3], v[52:53] op_sel_hi:[0,1]
	v_pk_mul_f32 v[8:9], v[10:11], v[8:9]
	v_pk_mul_f32 v[52:53], v[2:3], v[78:79] op_sel_hi:[0,1]
	v_cvt_pk_bf16_f32 v15, v8, v9
	global_store_dwordx4 v[44:45], v[12:15], off offset:64
	v_mov_b64_e32 v[8:9], v[186:187]
	v_mov_b64_e32 v[10:11], v[188:189]
	s_nop 0
	v_mov_b64_e32 v[12:13], v[170:171]
	v_mov_b64_e32 v[14:15], v[172:173]
	v_pk_mul_f32 v[12:13], v[12:13], v[52:53]
	v_pk_mul_f32 v[14:15], v[14:15], v[50:51]
	v_cvt_pk_bf16_f32 v12, v12, v13
	v_cvt_pk_bf16_f32 v13, v14, v15
	v_pk_mul_f32 v[14:15], v[2:3], v[72:73] op_sel_hi:[0,1]
	v_pk_mul_f32 v[8:9], v[14:15], v[8:9]
	s_nop 0
	v_cvt_pk_bf16_f32 v14, v8, v9
	v_pk_mul_f32 v[8:9], v[2:3], v[48:49] op_sel_hi:[0,1]
	v_pk_mul_f32 v[8:9], v[8:9], v[10:11]
	s_nop 0
	v_cvt_pk_bf16_f32 v15, v8, v9
	global_store_dwordx4 v[44:45], v[12:15], off offset:80
	v_mov_b64_e32 v[8:9], v[194:195]
	v_mov_b64_e32 v[10:11], v[196:197]
	s_nop 0
	v_mov_b64_e32 v[12:13], v[190:191]
	v_mov_b64_e32 v[14:15], v[192:193]
	v_pk_mul_f32 v[12:13], v[46:47], v[12:13]
	v_pk_mul_f32 v[14:15], v[20:21], v[14:15]
	v_cvt_pk_bf16_f32 v12, v12, v13
	v_cvt_pk_bf16_f32 v13, v14, v15
	v_pk_mul_f32 v[14:15], v[2:3], v[18:19] op_sel_hi:[0,1]
	v_pk_mul_f32 v[8:9], v[14:15], v[8:9]
	s_nop 0
	v_cvt_pk_bf16_f32 v14, v8, v9
	v_pk_mul_f32 v[8:9], v[2:3], v[16:17] op_sel_hi:[0,1]
	v_pk_mul_f32 v[8:9], v[8:9], v[10:11]
	v_pk_mul_f32 v[16:17], v[2:3], v[26:27] op_sel_hi:[0,1]
	v_cvt_pk_bf16_f32 v15, v8, v9
	global_store_dwordx4 v[44:45], v[12:15], off offset:96
	v_mov_b64_e32 v[8:9], v[202:203]
	v_mov_b64_e32 v[10:11], v[204:205]
	s_nop 0
	v_mov_b64_e32 v[12:13], v[198:199]
	v_mov_b64_e32 v[14:15], v[200:201]
	v_pk_mul_f32 v[12:13], v[16:17], v[12:13]
	v_pk_mul_f32 v[4:5], v[4:5], v[14:15]
	v_cvt_pk_bf16_f32 v12, v12, v13
	v_cvt_pk_bf16_f32 v13, v4, v5
	v_pk_mul_f32 v[4:5], v[2:3], v[22:23] op_sel_hi:[0,1]
	v_pk_mul_f32 v[4:5], v[4:5], v[8:9]
	s_nop 0
	v_cvt_pk_bf16_f32 v14, v4, v5
	v_pk_mul_f32 v[4:5], v[2:3], v[6:7] op_sel_hi:[0,1]
	v_pk_mul_f32 v[4:5], v[4:5], v[10:11]
	v_add_u32_e32 v2, 0x200, v121
	v_cvt_pk_bf16_f32 v15, v4, v5
	v_mov_b32_e32 v121, v2
	global_store_dwordx4 v[44:45], v[12:15], off offset:112
	s_andn2_b64 exec, exec, s[22:23]
	s_cbranch_execnz .LBB0_690
	s_branch .LBB0_687

; #define LAS __attribute__((address_space(3)))
; __device__ __forceinline__ unsigned f2bf(float f) { unsigned u = __float_as_uint(f); return (u + 0x7fffu + ((u >> 16) & 1u)) >> 16; }
; __device__ __forceinline__ unsigned pk2(float lo, float hi) { return pg8::cvt_pk_bf16(lo, hi); }
; __device__ __forceinline__ void nsa_compress3_phase(const bf16* z, const bf16* phit, const float* pec, const float* kg, bf16* kch, bf16* kcl, bf16* vct, LAS unsigned char* lds, int tid, int u0, int ustride) {
;     ...
;         for (int st = 0; st < 16; ++st) { const int sidx = wave * 16 + st, l = sidx >> 2, d0 = (sidx & 3) * 16;
;             const bf16x8 af = *(const bf16x8*)(ap + (size_t)l * ZP + d0);
;             const bf16x8 b0 = *(const bf16x8*)(bp + 16 * sidx), b1 = *(const bf16x8*)(bp + 32 * 2048 + 16 * sidx);
;             acc0 = MFMA32(af, b0, acc0); acc1 = MFMA32(af, b1, acc1); }
; #pragma unroll
;         for (int r = 0; r < 16; ++r) { part[(wave * 32 + crow(r, hi)) * 64 + r32] = acc0[r]; part[(wave * 32 + crow(r, hi)) * 64 + 32 + r32] = acc1[r]; }
;         __syncthreads();
;         { const int row = tid >> 4, e0 = (tid & 15) * 4; f32x4 v = *(const f32x4*)(pec + kv * 64 + e0);
; #pragma unroll
;           for (int w = 0; w < 8; ++w) v += *(const LAS f32x4*)(part + (w * 32 + row) * 64 + e0);
;           const int nn = 32 * mt + row; const size_t bg = (size_t)(b * 4 + g);
;           if (kv == 0) {
;               float ss = (v[0] * v[0] + v[1] * v[1]) + (v[2] * v[2] + v[3] * v[3]);
;               ss += __shfl_xor(ss, 1); ss += __shfl_xor(ss, 2); ss += __shfl_xor(ss, 4); ss += __shfl_xor(ss, 8);
;               const float rs = rsqrtf(ss * (1.0f / 64.0f) + EPS); const f32x4 gn = *(const f32x4*)(kg + e0);
;               unsigned hw[4]; float lo[4];
; #pragma unroll
;               for (int j = 0; j < 4; ++j) { const float kn = (nn < NCMP) ? v[j] * rs * gn[j] : 0.f; hw[j] = f2bf(kn); lo[j] = kn - __uint_as_float(hw[j] << 16); }
;               u32x2 oh, ol; oh.x = hw[0] | (hw[1] << 16); oh.y = hw[2] | (hw[3] << 16); ol.x = pk2(lo[0], lo[1]); ol.y = pk2(lo[2], lo[3]);
;               *(u32x2*)(kch + (bg * 128 + nn) * 64 + e0) = oh; *(u32x2*)(kcl + (bg * 128 + nn) * 64 + e0) = ol;
;           } else {
; #pragma unroll
;               for (int j = 0; j < 4; ++j) vct[(bg * 64 + e0 + j) * 128 + vpos(nn)] = (bf16)f2bf((nn < NCMP) ? v[j] : 0.f);
.LBB0_695:
	v_lshl_add_u64 v[64:65], v[48:49], 0, s[8:9]
	s_mov_b32 s15, 0x600000
	v_add_co_u32_e32 v68, vcc, s15, v64
	s_mov_b32 s15, 0x620000
	s_nop 0
	v_addc_co_u32_e32 v69, vcc, 0, v65, vcc
	v_add_co_u32_e32 v70, vcc, s15, v64
	s_nop 1
	v_addc_co_u32_e32 v71, vcc, 0, v65, vcc
	s_ashr_i32 s15, s7, 2
	v_mad_i64_i32 v[72:73], s[16:17], s15, v229, v[50:51]
	s_add_i32 s15, s7, 1
	s_ashr_i32 s15, s15, 2
	v_mad_i64_i32 v[74:75], s[16:17], s15, v229, v[50:51]
	s_add_i32 s15, s7, 2
	s_ashr_i32 s15, s15, 2
	v_mad_i64_i32 v[76:77], s[16:17], s15, v229, v[50:51]
	s_add_i32 s15, s7, 3
	s_ashr_i32 s15, s15, 2
	v_mad_i64_i32 v[78:79], s[16:17], s15, v229, v[50:51]
	global_load_dwordx4 v[80:83], v[72:73], off
	global_load_dwordx4 v[96:99], v[68:69], off
	global_load_dwordx4 v[112:115], v[70:71], off
	global_load_dwordx4 v[84:87], v[74:75], off offset:32
	global_load_dwordx4 v[100:103], v[68:69], off offset:32
	global_load_dwordx4 v[116:119], v[70:71], off offset:32
	global_load_dwordx4 v[88:91], v[76:77], off offset:64
	global_load_dwordx4 v[104:107], v[68:69], off offset:64
	global_load_dwordx4 v[120:123], v[70:71], off offset:64
	global_load_dwordx4 v[92:95], v[78:79], off offset:96
	global_load_dwordx4 v[108:111], v[68:69], off offset:96
	global_load_dwordx4 v[124:127], v[70:71], off offset:96
	s_add_i32 s7, s7, 4
	s_add_u32 s8, s8, 0x80
	s_addc_u32 s9, s9, 0
	s_cmpk_eq_i32 s8, 0x200
	s_waitcnt vmcnt(10)
	v_mfma_f32_32x32x16_bf16 v[4:19], v[80:83], v[96:99], v[4:19]
	s_waitcnt vmcnt(9)
	v_mfma_f32_32x32x16_bf16 v[20:35], v[80:83], v[112:115], v[20:35]
	s_waitcnt vmcnt(7)
	v_mfma_f32_32x32x16_bf16 v[4:19], v[84:87], v[100:103], v[4:19]
	s_waitcnt vmcnt(6)
	v_mfma_f32_32x32x16_bf16 v[20:35], v[84:87], v[116:119], v[20:35]
	s_waitcnt vmcnt(4)
	v_mfma_f32_32x32x16_bf16 v[4:19], v[88:91], v[104:107], v[4:19]
	s_waitcnt vmcnt(3)
	v_mfma_f32_32x32x16_bf16 v[20:35], v[88:91], v[120:123], v[20:35]
	s_waitcnt vmcnt(1)
	v_mfma_f32_32x32x16_bf16 v[4:19], v[92:95], v[108:111], v[4:19]
	s_waitcnt vmcnt(0)
	v_mfma_f32_32x32x16_bf16 v[20:35], v[92:95], v[124:127], v[20:35]
	s_cbranch_scc0 .LBB0_695
	s_nop 10
	ds_write2_b32 v52, v4, v20 offset1:32
	ds_write2_b32 v52, v5, v21 offset0:64 offset1:96
	ds_write2_b32 v52, v6, v22 offset0:128 offset1:160
	ds_write2_b32 v52, v7, v23 offset0:192 offset1:224
	v_add_u32_e32 v4, 0x800, v52
	ds_write2_b32 v4, v8, v24 offset1:32
	ds_write2_b32 v4, v9, v25 offset0:64 offset1:96
	ds_write2_b32 v4, v10, v26 offset0:128 offset1:160
	ds_write2_b32 v4, v11, v27 offset0:192 offset1:224
	v_add_u32_e32 v4, 0x1000, v52
	ds_write2_b32 v4, v12, v28 offset1:32
	ds_write2_b32 v4, v13, v29 offset0:64 offset1:96
	ds_write2_b32 v4, v14, v30 offset0:128 offset1:160
	ds_write2_b32 v4, v15, v31 offset0:192 offset1:224
	v_add_u32_e32 v4, 0x1800, v52
	s_lshl_b32 s68, s14, 8
	ds_write2_b32 v4, v16, v32 offset1:32
	ds_write2_b32 v4, v17, v33 offset0:64 offset1:96
	ds_write2_b32 v4, v18, v34 offset0:128 offset1:160
	ds_write2_b32 v4, v19, v35 offset0:192 offset1:224
	v_lshl_add_u64 v[4:5], v[36:37], 0, s[68:69]
	s_waitcnt lgkmcnt(0)
	s_barrier
	global_load_dwordx4 v[4:7], v[4:5], off
	ds_read_b128 v[8:11], v54
	s_lshl_b32 s6, s6, 2
	s_or_b32 s6, s6, s10
	s_and_b64 vcc, exec, s[4:5]
	s_movk_i32 s4, 0x7f
	s_ashr_i32 s7, s6, 31
	s_waitcnt vmcnt(0) lgkmcnt(0)
	v_pk_add_f32 v[10:11], v[6:7], v[10:11]
	v_pk_add_f32 v[8:9], v[4:5], v[8:9]
	ds_read_b128 v[4:7], v54 offset:8192
	s_waitcnt lgkmcnt(0)
	v_pk_add_f32 v[10:11], v[10:11], v[6:7]
	v_pk_add_f32 v[8:9], v[8:9], v[4:5]
	ds_read_b128 v[4:7], v54 offset:16384
	s_waitcnt lgkmcnt(0)
	v_pk_add_f32 v[10:11], v[10:11], v[6:7]
	v_pk_add_f32 v[8:9], v[8:9], v[4:5]
	ds_read_b128 v[4:7], v54 offset:24576
	s_waitcnt lgkmcnt(0)
	v_pk_add_f32 v[10:11], v[10:11], v[6:7]
	v_pk_add_f32 v[8:9], v[8:9], v[4:5]
	ds_read_b128 v[4:7], v54 offset:32768
	s_waitcnt lgkmcnt(0)
	v_pk_add_f32 v[10:11], v[10:11], v[6:7]
	v_pk_add_f32 v[8:9], v[8:9], v[4:5]
	ds_read_b128 v[4:7], v54 offset:40960
	s_waitcnt lgkmcnt(0)
	v_pk_add_f32 v[10:11], v[10:11], v[6:7]
	v_pk_add_f32 v[8:9], v[8:9], v[4:5]
	ds_read_b128 v[4:7], v54 offset:49152
	s_waitcnt lgkmcnt(0)
	v_pk_add_f32 v[10:11], v[10:11], v[6:7]
	v_pk_add_f32 v[8:9], v[8:9], v[4:5]
	ds_read_b128 v[4:7], v54 offset:57344
	s_waitcnt lgkmcnt(0)
	v_pk_add_f32 v[8:9], v[8:9], v[4:5]
	v_add_u32_e32 v4, s11, v53
	v_pk_add_f32 v[6:7], v[10:11], v[6:7]
	s_mov_b64 s[10:11], -1
	v_cmp_gt_i32_e64 s[8:9], s4, v4
	s_cbranch_vccz .LBB0_698
	v_lshlrev_b32_e32 v10, 1, v4
	v_and_b32_e32 v5, -13, v4
	v_and_b32_e32 v10, 8, v10
	v_or3_b32 v10, v5, v55, v10
	v_readlane_b32 s4, v252, 31
	v_ashrrev_i32_e32 v11, 31, v10
	v_readlane_b32 s5, v252, 32
	v_cndmask_b32_e64 v5, 0, v8, s[8:9]
	v_bfe_u32 v12, v5, 16, 1
	v_lshl_add_u64 v[10:11], v[10:11], 1, s[4:5]
	s_lshl_b64 s[4:5], s[6:7], 14
	s_movk_i32 s10, 0x7fff
	v_lshl_add_u64 v[10:11], v[10:11], 0, s[4:5]
	v_add3_u32 v5, v5, v12, s10
	v_lshl_add_u64 v[10:11], v[10:11], 0, v[44:45]
	global_store_short_d16_hi v[10:11], v5, off
	v_cndmask_b32_e64 v5, 0, v9, s[8:9]
	v_bfe_u32 v12, v5, 16, 1
	v_add3_u32 v5, v5, v12, s10
	global_store_short_d16_hi v[10:11], v5, off offset:256
	v_cndmask_b32_e64 v5, 0, v6, s[8:9]
	v_bfe_u32 v12, v5, 16, 1
	v_add3_u32 v5, v5, v12, s10
	global_store_short_d16_hi v[10:11], v5, off offset:512
	v_cndmask_b32_e64 v5, 0, v7, s[8:9]
	v_bfe_u32 v12, v5, 16, 1
	v_add3_u32 v5, v5, v12, s10
	s_mov_b64 s[10:11], 0
	global_store_short_d16_hi v[10:11], v5, off offset:768
